# v27 plus phase_norm next-row loads prefetched one iteration ahead
# baseline (speedup 1.0000x reference)
; DI int bid_() { return (int)blockIdx.x; }
; DI void phase_norm(const float* X, const float* nw, bf16_t* H, const float* Wg, int ldw, int col0, float* GATE, lptr lds) {
;     ...
;     __syncthreads();
;     f32x4 wv[4];
; #pragma unroll
;     for (int k = 0; k < 4; ++k) wv[k] = *(const f32x4*)(nw + 4 * lane + 256 * k);
;     for (int rowf = bid_() * 8 + wave; rowf < MTOK; rowf += gridDim.x * 8) {
;         const int row = MTOK - 1 - rowf;
;         f32x4 x[4]; float ss = 0.f;
; #pragma unroll
;         for (int k = 0; k < 4; ++k) { x[k] = *(const f32x4*)(X + (size_t)row * DM + 4 * lane + 256 * k); ss += x[k][0] * x[k][0] + x[k][1] * x[k][1] + x[k][2] * x[k][2] + x[k][3] * x[k][3]; }
.LBB0_90:
	s_or_b64 exec, exec, s[0:1]
	v_readlane_b32 s36, v252, 18
	v_ashrrev_i32_e32 v0, 6, v2
	v_readlane_b32 s0, v250, 55
	s_cmp_eq_u32 s70, 0
	v_readlane_b32 s37, v252, 19
	v_add_u32_e32 v74, s0, v0
	s_mov_b32 s0, 0x8000
	s_cselect_b32 s23, s37, s89
	s_cselect_b32 s22, s36, s88
	s_lshl_b32 s82, s70, 10
	v_cmp_gt_i32_e32 vcc, s0, v74
	v_readlane_b32 s38, v252, 20
	v_readlane_b32 s39, v252, 21
	v_readlane_b32 s40, v252, 22
	v_readlane_b32 s41, v252, 23
	v_readlane_b32 s42, v252, 24
	v_readlane_b32 s43, v252, 25
	v_readlane_b32 s44, v252, 26
	v_readlane_b32 s45, v252, 27
	v_readlane_b32 s46, v252, 28
	v_readlane_b32 s47, v252, 29
	v_readlane_b32 s48, v252, 30
	v_readlane_b32 s49, v252, 31
	v_readlane_b32 s50, v252, 32
	v_readlane_b32 s51, v252, 33
	s_waitcnt lgkmcnt(0)
	s_barrier
	s_and_saveexec_b64 s[58:59], vcc
	s_cbranch_execz .LBB0_99
	v_readlane_b32 s36, v252, 18
	s_lshl_b64 s[0:1], s[82:83], 2
	v_readlane_b32 s42, v252, 24
	v_readlane_b32 s43, v252, 25
	s_add_u32 s0, s42, s0
	v_and_b32_e32 v18, 63, v2
	s_addc_u32 s1, s43, s1
	v_lshlrev_b32_e32 v36, 4, v18
	global_load_dwordx4 v[2:5], v36, s[0:1] offset:2048
	global_load_dwordx4 v[6:9], v36, s[0:1] offset:3072
	global_load_dwordx4 v[10:13], v36, s[0:1]
	global_load_dwordx4 v[14:17], v36, s[0:1] offset:1024
	v_readlane_b32 s38, v252, 20
	v_readlane_b32 s39, v252, 21
	v_mov_b32_e32 v37, v1
	v_lshlrev_b32_e32 v0, 3, v18
	v_cmp_eq_u32_e64 s[38:39], 0, v18
	v_lshl_add_u64 v[38:39], s[22:23], 0, v[36:37]
	v_lshl_add_u64 v[40:41], s[96:97], 0, v[0:1]
	s_mov_b64 s[60:61], 0
	v_readlane_b32 s37, v252, 19
	v_readlane_b32 s40, v252, 22
	v_readlane_b32 s41, v252, 23
	v_readlane_b32 s44, v252, 26
	v_readlane_b32 s45, v252, 27
	v_readlane_b32 s46, v252, 28
	v_readlane_b32 s47, v252, 29
	v_readlane_b32 s48, v252, 30
	v_readlane_b32 s49, v252, 31
	v_readlane_b32 s50, v252, 32
	v_readlane_b32 s51, v252, 33
	s_waitcnt vmcnt(3)
	v_mov_b32_e32 v42, v5
	s_waitcnt vmcnt(2)
	v_mov_b32_e32 v43, v9
	v_mov_b32_e32 v5, v8
	v_mov_b32_e32 v44, v2
	v_mov_b32_e32 v45, v6
	v_mov_b32_e32 v6, v3
	s_waitcnt vmcnt(1)
	v_mov_b32_e32 v2, v13
	s_waitcnt vmcnt(0)
	v_mov_b32_e32 v3, v17
	v_mov_b32_e32 v13, v16
	v_mov_b32_e32 v46, v10
	v_mov_b32_e32 v47, v14
	v_mov_b32_e32 v14, v11
	v_sub_u32_e32 v124, 0x7fff, v74
	v_mov_b32_e32 v125, 0
	v_lshlrev_b64 v[126:127], 12, v[124:125]
	v_lshl_add_u64 v[126:127], v[38:39], 0, v[126:127]
	global_load_dwordx4 v[108:111], v[126:127], off
	global_load_dwordx4 v[112:115], v[126:127], off offset:1024
	global_load_dwordx4 v[116:119], v[126:127], off offset:2048
	global_load_dwordx4 v[120:123], v[126:127], off offset:3072
	s_waitcnt vmcnt(0)
	s_branch .LBB0_94

; DI unsigned pk2(float lo, float hi) { f32x2_t v = {lo, hi}; bf16x2_t b = __builtin_convertvector(v, bf16x2_t); return __builtin_bit_cast(unsigned, b); }
; DI float wave_sum(float v) { v += shx(v, 32); v += shx(v, 16); v += shx(v, 8); v += shx(v, 4); v += shx(v, 2); v += shx(v, 1); return v; }
; DI int bid_() { return (int)blockIdx.x; }
; DI void phase_norm(const float* X, const float* nw, bf16_t* H, const float* Wg, int ldw, int col0, float* GATE, lptr lds) {
;     ...
;     for (int rowf = bid_() * 8 + wave; rowf < MTOK; rowf += gridDim.x * 8) {
;         const int row = MTOK - 1 - rowf;
;         f32x4 x[4]; float ss = 0.f;
; #pragma unroll
;         for (int k = 0; k < 4; ++k) { x[k] = *(const f32x4*)(X + (size_t)row * DM + 4 * lane + 256 * k); ss += x[k][0] * x[k][0] + x[k][1] * x[k][1] + x[k][2] * x[k][2] + x[k][3] * x[k][3]; }
;         ss = wave_sum(ss);
;         const float rstd = rsqrtf(ss * (1.f / 1024.f) + EPS);
; #pragma unroll
;         for (int k = 0; k < 4; ++k) { for (int e = 0; e < 4; ++e) x[k][e] = x[k][e] * rstd * wv[k][e];
;             u32x2 w; w.x = pk2(x[k][0], x[k][1]); w.y = pk2(x[k][2], x[k][3]); *(u32x2*)(H + (size_t)row * DM + 4 * lane + 256 * k) = w; }
.LBB0_94:
	v_sub_u32_e32 v0, 0x7fff, v74
	s_waitcnt vmcnt(4)
	v_mov_b32_e32 v8, v108
	v_mov_b32_e32 v9, v109
	v_mov_b32_e32 v10, v110
	v_mov_b32_e32 v11, v111
	v_mov_b32_e32 v16, v112
	v_mov_b32_e32 v17, v113
	v_mov_b32_e32 v18, v114
	v_mov_b32_e32 v19, v115
	v_mov_b32_e32 v20, v116
	v_mov_b32_e32 v21, v117
	v_mov_b32_e32 v22, v118
	v_mov_b32_e32 v23, v119
	v_mov_b32_e32 v24, v120
	v_mov_b32_e32 v25, v121
	v_mov_b32_e32 v26, v122
	v_mov_b32_e32 v27, v123
	v_add_u32_e32 v124, s71, v74
	v_sub_u32_e32 v124, 0x7fff, v124
	v_cmp_gt_i32_e32 vcc, 0, v124
	s_cbranch_vccnz .Lmy_norm_nopf
	v_lshlrev_b64 v[126:127], 12, v[124:125]
	v_lshl_add_u64 v[126:127], v[38:39], 0, v[126:127]
	global_load_dwordx4 v[108:111], v[126:127], off
	global_load_dwordx4 v[112:115], v[126:127], off offset:1024
	global_load_dwordx4 v[116:119], v[126:127], off offset:2048
	global_load_dwordx4 v[120:123], v[126:127], off offset:3072
.Lmy_norm_nopf:
	v_mov_b32_e32 v28, v194
	s_andn2_b64 vcc, exec, s[56:57]
	v_lshlrev_b32_e32 v28, 2, v28
	v_bitop3_b32 v32, v28, s29, v199 bitop3:0x6c
	v_mov_b32_e32 v28, v8
	v_mov_b32_e32 v29, v16
	v_mov_b32_e32 v16, v9
	v_mov_b32_e32 v8, v10
	v_mov_b32_e32 v9, v18
	v_mov_b32_e32 v18, v11
	v_mov_b32_e32 v10, v20
	v_mov_b32_e32 v11, v24
	v_mov_b32_e32 v24, v21
	v_mov_b32_e32 v20, v22
	v_mov_b32_e32 v21, v26
	v_mov_b32_e32 v26, v23
	v_pk_mul_f32 v[22:23], v[16:17], v[16:17]
	v_pk_mul_f32 v[30:31], v[24:25], v[24:25]
	v_pk_fma_f32 v[22:23], v[28:29], v[28:29], v[22:23]
	v_pk_fma_f32 v[30:31], v[10:11], v[10:11], v[30:31]
	v_pk_fma_f32 v[22:23], v[8:9], v[8:9], v[22:23]
	v_pk_fma_f32 v[30:31], v[20:21], v[20:21], v[30:31]
	v_pk_fma_f32 v[22:23], v[18:19], v[18:19], v[22:23]
	v_pk_fma_f32 v[30:31], v[26:27], v[26:27], v[30:31]
	v_add_f32_e32 v22, v22, v23
	v_add_f32_e32 v22, v22, v30
	v_add_f32_e32 v22, v22, v31
	ds_bpermute_b32 v23, v32, v22
	v_mov_b32_e32 v30, v194
	s_waitcnt lgkmcnt(0)
	v_add_f32_e32 v22, v22, v23
	v_lshlrev_b32_e32 v30, 2, v30
	v_bitop3_b32 v30, v30, 64, v199 bitop3:0x6c
	ds_bpermute_b32 v23, v30, v22
	v_mov_b32_e32 v30, v194
	s_waitcnt lgkmcnt(0)
	v_add_f32_e32 v22, v22, v23
	v_lshlrev_b32_e32 v30, 2, v30
	v_bitop3_b32 v30, v30, 32, v199 bitop3:0x6c
	ds_bpermute_b32 v23, v30, v22
	v_mov_b32_e32 v30, v194
	s_waitcnt lgkmcnt(0)
	v_add_f32_e32 v22, v22, v23
	v_lshlrev_b32_e32 v30, 2, v30
	v_bitop3_b32 v30, v30, 16, v199 bitop3:0x6c
	ds_bpermute_b32 v23, v30, v22
	v_mov_b32_e32 v30, v194
	s_waitcnt lgkmcnt(0)
	v_add_f32_e32 v22, v22, v23
	v_lshlrev_b32_e32 v30, 2, v30
	v_bitop3_b32 v30, v30, 8, v199 bitop3:0x6c
	ds_bpermute_b32 v23, v30, v22
	v_mov_b32_e32 v30, v194
	s_waitcnt lgkmcnt(0)
	v_add_f32_e32 v22, v22, v23
	v_lshlrev_b32_e32 v30, 2, v30
	v_bitop3_b32 v30, v30, 4, v199 bitop3:0x6c
	ds_bpermute_b32 v23, v30, v22
	s_waitcnt lgkmcnt(0)
	v_add_f32_e32 v22, v22, v23
	v_fmamk_f32 v22, v22, 0x3a800000, v195
	v_mul_f32_e32 v23, 0x4b800000, v22
	v_cmp_gt_f32_e64 s[0:1], s72, v22
	s_nop 1
	v_cndmask_b32_e64 v22, v22, v23, s[0:1]
	v_rsq_f32_e32 v30, v22
	v_lshlrev_b64 v[22:23], 11, v[0:1]
	v_lshl_add_u64 v[22:23], v[40:41], 0, v[22:23]
	v_mul_f32_e32 v31, 0x45800000, v30
	v_cndmask_b32_e64 v30, v30, v31, s[0:1]
	v_pk_mul_f32 v[16:17], v[16:17], v[30:31] op_sel_hi:[1,0]
	v_pk_mul_f32 v[18:19], v[18:19], v[30:31] op_sel_hi:[1,0]
	v_pk_mul_f32 v[28:29], v[28:29], v[30:31] op_sel_hi:[1,0]
	v_pk_mul_f32 v[8:9], v[8:9], v[30:31] op_sel_hi:[1,0]
	v_pk_mul_f32 v[24:25], v[24:25], v[30:31] op_sel_hi:[1,0]
	v_pk_mul_f32 v[26:27], v[26:27], v[30:31] op_sel_hi:[1,0]
	v_pk_mul_f32 v[10:11], v[10:11], v[30:31] op_sel_hi:[1,0]
	v_pk_mul_f32 v[20:21], v[20:21], v[30:31] op_sel_hi:[1,0]
	v_pk_mul_f32 v[62:63], v[46:47], v[28:29]
	v_pk_mul_f32 v[66:67], v[14:15], v[16:17]
	v_pk_mul_f32 v[60:61], v[12:13], v[8:9]
	v_pk_mul_f32 v[58:59], v[2:3], v[18:19]
	v_pk_mul_f32 v[52:53], v[44:45], v[10:11]
	v_pk_mul_f32 v[54:55], v[6:7], v[24:25]
	v_pk_mul_f32 v[50:51], v[4:5], v[20:21]
	v_pk_mul_f32 v[48:49], v[42:43], v[26:27]
	v_cvt_pk_bf16_f32 v10, v62, v66
	v_cvt_pk_bf16_f32 v11, v60, v58
	v_cvt_pk_bf16_f32 v16, v63, v67
	v_cvt_pk_bf16_f32 v17, v61, v59
	v_cvt_pk_bf16_f32 v18, v52, v54
	v_cvt_pk_bf16_f32 v19, v50, v48
	v_cvt_pk_bf16_f32 v20, v53, v55
	v_cvt_pk_bf16_f32 v21, v51, v49
	global_store_dwordx2 v[22:23], v[10:11], off
	global_store_dwordx2 v[22:23], v[16:17], off offset:512
	global_store_dwordx2 v[22:23], v[18:19], off offset:1024
	global_store_dwordx2 v[22:23], v[20:21], off offset:1536
	s_cbranch_vccnz .LBB0_93
; DI void phase_norm(const float* X, const float* nw, bf16_t* H, const float* Wg, int ldw, int col0, float* GATE, lptr lds) {
;     ...
;         if (Wg) {
;             float g[8]; for (int e = 0; e < 8; ++e) g[e] = 0.f;
; #pragma unroll
;             for (int k = 0; k < 4; ++k)
; #pragma unroll
;                 for (int q = 0; q < 8; ++q) { const f32x4 w4 = lld<f32x4>(lds, 32768 + (q * 1024 + 4 * lane + 256 * k) * 4);
;                     g[q] += x[k][0] * w4[0] + x[k][1] * w4[1] + x[k][2] * w4[2] + x[k][3] * w4[3]; }
	v_add_u32_e32 v37, 0, v36
	ds_read_b128 v[16:19], v37 offset:57344
	ds_read_b128 v[76:79], v37 offset:58368
	v_mov_b32_e32 v9, v66
	v_mov_b32_e32 v8, v62
	v_mov_b32_e32 v10, v60
	s_waitcnt lgkmcnt(1)
	v_mul_f32_e32 v20, v9, v17
	v_mov_b32_e32 v11, v58
	v_pk_fma_f32 v[8:9], v[8:9], v[16:17], v[20:21] op_sel_hi:[1,1,0]
	v_mul_f32_e32 v22, v58, v19
	v_pk_fma_f32 v[8:9], v[10:11], v[18:19], v[8:9]
	v_mov_b32_e32 v69, v67
	v_pk_add_f32 v[64:65], v[22:23], v[8:9] op_sel_hi:[0,1]
	ds_read_b128 v[28:31], v37 offset:32768
	ds_read_b128 v[24:27], v37 offset:33792
	ds_read_b128 v[32:35], v37 offset:36864
	ds_read_b128 v[20:23], v37 offset:37888
	ds_read_b128 v[16:19], v37 offset:40960
	ds_read_b128 v[8:11], v37 offset:41984
	ds_read_b128 v[80:83], v37 offset:61440
	ds_read_b128 v[84:87], v37 offset:62464
	v_mov_b32_e32 v68, v63
	s_waitcnt lgkmcnt(8)
	v_mul_f32_e32 v70, v69, v77
	v_pk_fma_f32 v[68:69], v[68:69], v[76:77], v[70:71] op_sel_hi:[1,1,0]
	v_mov_b32_e32 v70, v61
	v_mov_b32_e32 v71, v59
	v_pk_fma_f32 v[68:69], v[70:71], v[78:79], v[68:69]
	v_mul_f32_e32 v70, v59, v79
	v_pk_add_f32 v[68:69], v[70:71], v[68:69] op_sel_hi:[0,1]
	s_waitcnt lgkmcnt(0)
	v_mov_b32_e32 v71, v84
	v_mov_b32_e32 v84, v81
	v_mov_b32_e32 v70, v80
	v_pk_mul_f32 v[76:77], v[66:67], v[84:85]
	v_mov_b32_e32 v73, v54
	v_pk_fma_f32 v[70:71], v[62:63], v[70:71], v[76:77]
	ds_read_b128 v[76:79], v37 offset:59392
	v_mov_b32_e32 v80, v82
	v_mov_b32_e32 v81, v86
	v_mov_b32_e32 v72, v52
	v_pk_fma_f32 v[70:71], v[60:61], v[80:81], v[70:71]
	v_mov_b32_e32 v86, v83
	ds_read_b128 v[80:83], v37 offset:60416
	s_waitcnt lgkmcnt(1)
	v_mul_f32_e32 v84, v73, v77
	v_pk_fma_f32 v[72:73], v[72:73], v[76:77], v[84:85] op_sel_hi:[1,1,0]
	v_mov_b32_e32 v76, v50
	v_mov_b32_e32 v77, v48
	v_pk_fma_f32 v[72:73], v[76:77], v[78:79], v[72:73]
	v_mul_f32_e32 v76, v48, v79
	v_pk_add_f32 v[72:73], v[76:77], v[72:73] op_sel_hi:[0,1]
	v_mov_b32_e32 v77, v32
	v_mov_b32_e32 v32, v29
	v_mov_b32_e32 v76, v28
	v_pk_mul_f32 v[28:29], v[66:67], v[32:33] op_sel_hi:[0,1]
	v_pk_fma_f32 v[28:29], v[62:63], v[76:77], v[28:29] op_sel_hi:[0,1,1]
	v_mov_b32_e32 v32, v30
	v_mov_b32_e32 v33, v34
	v_pk_fma_f32 v[28:29], v[60:61], v[32:33], v[28:29] op_sel_hi:[0,1,1]
	v_mov_b32_e32 v34, v31
	v_pk_fma_f32 v[32:33], v[58:59], v[34:35], v[28:29] op_sel_hi:[0,1,1]
	v_mov_b32_e32 v29, v20
	v_mov_b32_e32 v20, v25
	v_mov_b32_e32 v28, v24
	v_pk_mul_f32 v[20:21], v[66:67], v[20:21] op_sel:[1,0]
	v_pk_fma_f32 v[70:71], v[58:59], v[86:87], v[70:71]
	ds_read_b128 v[76:79], v37 offset:34816
	ds_read_b128 v[84:87], v37 offset:35840
	v_pk_fma_f32 v[20:21], v[62:63], v[28:29], v[20:21] op_sel:[1,0,0]
	v_mov_b32_e32 v34, v26
	v_mov_b32_e32 v35, v22
	v_mov_b32_e32 v22, v27
	ds_read_b128 v[24:27], v37 offset:38912
	ds_read_b128 v[28:31], v37 offset:39936
	v_pk_fma_f32 v[20:21], v[60:61], v[34:35], v[20:21] op_sel:[1,0,0]
	v_pk_add_f32 v[32:33], v[32:33], 0 op_sel_hi:[1,0]
	v_pk_fma_f32 v[20:21], v[58:59], v[22:23], v[20:21] op_sel:[1,0,0]
	v_mov_b32_e32 v57, v55
	v_pk_add_f32 v[88:89], v[32:33], v[20:21]
	s_waitcnt lgkmcnt(1)
	v_mov_b32_e32 v21, v24
	v_mov_b32_e32 v24, v77
	v_mov_b32_e32 v20, v76
	v_pk_mul_f32 v[22:23], v[54:55], v[24:25] op_sel_hi:[0,1]
	v_pk_fma_f32 v[24:25], v[52:53], v[20:21], v[22:23] op_sel_hi:[0,1,1]
	ds_read_b128 v[20:23], v37 offset:45056
	ds_read_b128 v[32:35], v37 offset:46080
	v_mov_b32_e32 v76, v78
	v_mov_b32_e32 v77, v26
	v_mov_b32_e32 v26, v79
	v_pk_fma_f32 v[24:25], v[50:51], v[76:77], v[24:25] op_sel_hi:[0,1,1]
	v_pk_fma_f32 v[24:25], v[48:49], v[26:27], v[24:25] op_sel_hi:[0,1,1]
	v_pk_add_f32 v[88:89], v[88:89], v[24:25]
	s_waitcnt lgkmcnt(2)
	v_mov_b32_e32 v25, v28
	v_mov_b32_e32 v28, v85
	s_waitcnt lgkmcnt(1)
	v_mov_b32_e32 v77, v20
	v_mov_b32_e32 v20, v17
	v_mov_b32_e32 v24, v84
	v_pk_mul_f32 v[26:27], v[54:55], v[28:29] op_sel:[1,0]
	v_mov_b32_e32 v76, v16
	v_pk_mul_f32 v[16:17], v[66:67], v[20:21] op_sel_hi:[0,1]
	v_pk_fma_f32 v[24:25], v[52:53], v[24:25], v[26:27] op_sel:[1,0,0]
	v_mov_b32_e32 v26, v86
	v_mov_b32_e32 v27, v30
	v_pk_fma_f32 v[16:17], v[62:63], v[76:77], v[16:17] op_sel_hi:[0,1,1]
	v_mov_b32_e32 v20, v18
	v_mov_b32_e32 v21, v22
	v_pk_fma_f32 v[24:25], v[50:51], v[26:27], v[24:25] op_sel:[1,0,0]
	v_mov_b32_e32 v30, v87
	v_pk_fma_f32 v[20:21], v[60:61], v[20:21], v[16:17] op_sel_hi:[0,1,1]
	v_mov_b32_e32 v22, v19
	v_pk_fma_f32 v[84:85], v[48:49], v[30:31], v[24:25] op_sel:[1,0,0]
	ds_read_b128 v[24:27], v37 offset:43008
	ds_read_b128 v[28:31], v37 offset:44032
	ds_read_b128 v[16:19], v37 offset:47104
	ds_read_b128 v[76:79], v37 offset:48128
	v_pk_fma_f32 v[86:87], v[58:59], v[22:23], v[20:21] op_sel_hi:[0,1,1]
	s_waitcnt lgkmcnt(4)
	v_mov_b32_e32 v21, v32
	v_mov_b32_e32 v32, v9
	v_mov_b32_e32 v20, v8
	v_pk_mul_f32 v[8:9], v[66:67], v[32:33] op_sel:[1,0]
	v_mov_b32_e32 v56, v53
	v_pk_fma_f32 v[8:9], v[62:63], v[20:21], v[8:9] op_sel:[1,0,0]
	v_mov_b32_e32 v20, v10
	v_mov_b32_e32 v21, v34
	v_pk_fma_f32 v[8:9], v[60:61], v[20:21], v[8:9] op_sel:[1,0,0]
	v_mov_b32_e32 v34, v11
	v_pk_fma_f32 v[10:11], v[58:59], v[34:35], v[8:9] op_sel:[1,0,0]
	s_waitcnt lgkmcnt(1)
	v_mov_b32_e32 v9, v16
	v_mov_b32_e32 v16, v25
	v_mov_b32_e32 v8, v24
	v_pk_mul_f32 v[16:17], v[54:55], v[16:17] op_sel_hi:[0,1]
	v_pk_fma_f32 v[8:9], v[52:53], v[8:9], v[16:17] op_sel_hi:[0,1,1]
	v_mov_b32_e32 v16, v26
	v_mov_b32_e32 v17, v18
	v_pk_fma_f32 v[8:9], v[50:51], v[16:17], v[8:9] op_sel_hi:[0,1,1]
	v_mov_b32_e32 v18, v27
	ds_read_b128 v[20:23], v37 offset:49152
	ds_read_b128 v[32:35], v37 offset:50176
	v_pk_fma_f32 v[90:91], v[48:49], v[18:19], v[8:9] op_sel_hi:[0,1,1]
	ds_read_b128 v[16:19], v37 offset:53248
	ds_read_b128 v[24:27], v37 offset:54272
	v_pk_add_f32 v[8:9], v[88:89], v[84:85]
	v_pk_add_f32 v[84:85], v[86:87], 0 op_sel_hi:[1,0]
	v_mov_b32_e32 v65, v70
	v_pk_add_f32 v[10:11], v[84:85], v[10:11]
	s_waitcnt lgkmcnt(4)
; DI float wave_sum(float v) { v += shx(v, 32); v += shx(v, 16); v += shx(v, 8); v += shx(v, 4); v += shx(v, 2); v += shx(v, 1); return v; }
; DI void phase_norm(const float* X, const float* nw, bf16_t* H, const float* Wg, int ldw, int col0, float* GATE, lptr lds) {
;     ...
;             for (int k = 0; k < 4; ++k)
; #pragma unroll
;                 for (int q = 0; q < 8; ++q) { const f32x4 w4 = lld<f32x4>(lds, 32768 + (q * 1024 + 4 * lane + 256 * k) * 4);
;                     g[q] += x[k][0] * w4[0] + x[k][1] * w4[1] + x[k][2] * w4[2] + x[k][3] * w4[3]; }
;             for (int e = 0; e < 8; ++e) g[e] = wave_sum(g[e]);
	v_mov_b32_e32 v85, v76
	v_mov_b32_e32 v76, v29
	v_mov_b32_e32 v84, v28
	v_pk_mul_f32 v[28:29], v[54:55], v[76:77] op_sel:[1,0]
	v_mov_b32_e32 v76, v30
	v_pk_fma_f32 v[28:29], v[52:53], v[84:85], v[28:29] op_sel:[1,0,0]
	s_waitcnt lgkmcnt(1)
	v_mov_b32_e32 v85, v16
	v_mov_b32_e32 v16, v21
	v_mov_b32_e32 v84, v20
	v_pk_mul_f32 v[16:17], v[66:67], v[16:17] op_sel_hi:[0,1]
	v_mov_b32_e32 v77, v78
	v_pk_fma_f32 v[16:17], v[62:63], v[84:85], v[16:17] op_sel_hi:[0,1,1]
	v_mov_b32_e32 v20, v22
	v_mov_b32_e32 v21, v18
	v_pk_fma_f32 v[28:29], v[50:51], v[76:77], v[28:29] op_sel:[1,0,0]
	v_mov_b32_e32 v78, v31
	v_pk_fma_f32 v[16:17], v[60:61], v[20:21], v[16:17] op_sel_hi:[0,1,1]
	v_mov_b32_e32 v18, v23
	v_pk_add_f32 v[10:11], v[10:11], v[90:91]
	v_pk_fma_f32 v[28:29], v[48:49], v[78:79], v[28:29] op_sel:[1,0,0]
	v_pk_fma_f32 v[16:17], v[58:59], v[18:19], v[16:17] op_sel_hi:[0,1,1]
	s_waitcnt lgkmcnt(0)
	v_mov_b32_e32 v19, v24
	v_mov_b32_e32 v24, v33
	v_pk_add_f32 v[10:11], v[10:11], v[28:29]
	ds_read_b128 v[28:31], v37 offset:51200
	ds_read_b128 v[76:79], v37 offset:52224
	ds_read_b128 v[20:23], v37 offset:55296
	ds_read_b128 v[84:87], v37 offset:56320
	v_mov_b32_e32 v18, v32
	v_pk_mul_f32 v[24:25], v[66:67], v[24:25] op_sel:[1,0]
	v_pk_add_f32 v[16:17], v[16:17], 0 op_sel_hi:[1,0]
	v_pk_fma_f32 v[18:19], v[62:63], v[18:19], v[24:25] op_sel:[1,0,0]
	v_mov_b32_e32 v24, v34
	v_mov_b32_e32 v25, v26
	v_pk_fma_f32 v[18:19], v[60:61], v[24:25], v[18:19] op_sel:[1,0,0]
	v_mov_b32_e32 v26, v35
	v_pk_fma_f32 v[18:19], v[58:59], v[26:27], v[18:19] op_sel:[1,0,0]
	v_mov_b32_e32 v69, v71
	v_pk_add_f32 v[16:17], v[16:17], v[18:19]
	s_waitcnt lgkmcnt(1)
	v_mov_b32_e32 v19, v20
	v_mov_b32_e32 v20, v29
	v_mov_b32_e32 v18, v28
	v_pk_mul_f32 v[20:21], v[54:55], v[20:21] op_sel_hi:[0,1]
	v_pk_fma_f32 v[18:19], v[52:53], v[18:19], v[20:21] op_sel_hi:[0,1,1]
	v_mov_b32_e32 v20, v30
	v_mov_b32_e32 v21, v22
	v_pk_fma_f32 v[18:19], v[50:51], v[20:21], v[18:19] op_sel_hi:[0,1,1]
	v_mov_b32_e32 v22, v31
	v_pk_fma_f32 v[18:19], v[48:49], v[22:23], v[18:19] op_sel_hi:[0,1,1]
	v_pk_add_f32 v[16:17], v[16:17], v[18:19]
	s_waitcnt lgkmcnt(0)
	v_mov_b32_e32 v19, v84
	v_mov_b32_e32 v84, v77
	v_mov_b32_e32 v18, v76
	v_pk_mul_f32 v[20:21], v[54:55], v[84:85] op_sel:[1,0]
	v_mov_b32_e32 v28, v51
	v_pk_fma_f32 v[18:19], v[52:53], v[18:19], v[20:21] op_sel:[1,0,0]
	v_mov_b32_e32 v20, v78
	v_mov_b32_e32 v21, v86
	v_pk_fma_f32 v[18:19], v[50:51], v[20:21], v[18:19] op_sel:[1,0,0]
	v_mov_b32_e32 v86, v79
	v_pk_fma_f32 v[18:19], v[48:49], v[86:87], v[18:19] op_sel:[1,0,0]
	v_mov_b32_e32 v29, v49
	v_pk_add_f32 v[16:17], v[16:17], v[18:19]
	v_mul_f32_e32 v18, v57, v81
	v_pk_fma_f32 v[26:27], v[56:57], v[80:81], v[18:19] op_sel_hi:[1,1,0]
	ds_read_b128 v[18:21], v37 offset:63488
	ds_read_b128 v[22:25], v37 offset:64512
	v_pk_fma_f32 v[26:27], v[28:29], v[82:83], v[26:27]
	v_mul_f32_e32 v28, v49, v83
	v_pk_add_f32 v[26:27], v[28:29], v[26:27] op_sel_hi:[0,1]
	s_waitcnt lgkmcnt(1)
	v_mov_b32_e32 v28, v18
	s_waitcnt lgkmcnt(0)
	v_mov_b32_e32 v29, v22
	v_mov_b32_e32 v22, v19
	v_pk_mul_f32 v[18:19], v[54:55], v[22:23]
	v_mov_b32_e32 v22, v20
	v_pk_fma_f32 v[18:19], v[52:53], v[28:29], v[18:19]
	v_mov_b32_e32 v23, v24
	v_pk_fma_f32 v[18:19], v[50:51], v[22:23], v[18:19]
	v_mov_b32_e32 v24, v21
	v_pk_fma_f32 v[18:19], v[48:49], v[24:25], v[18:19]
	v_pk_add_f32 v[20:21], v[64:65], 0 op_sel_hi:[1,0]
	v_mov_b32_e32 v73, v18
	v_pk_add_f32 v[20:21], v[20:21], v[68:69]
	v_mov_b32_e32 v27, v19
	v_pk_add_f32 v[20:21], v[20:21], v[72:73]
	s_mov_b64 s[2:3], 0
	v_pk_add_f32 v[18:19], v[20:21], v[26:27]
	v_lshlrev_b32_e32 v106, 2, v194
	v_bitop3_b32 v100, v106, s29, v199 bitop3:0x6c
	v_bitop3_b32 v101, v106, 64, v199 bitop3:0x6c
	v_bitop3_b32 v102, v106, 32, v199 bitop3:0x6c
	v_bitop3_b32 v103, v106, 16, v199 bitop3:0x6c
	v_bitop3_b32 v104, v106, 8, v199 bitop3:0x6c
	v_bitop3_b32 v105, v106, 4, v199 bitop3:0x6c
	ds_bpermute_b32 v92, v100, v8
	ds_bpermute_b32 v93, v100, v9
	ds_bpermute_b32 v94, v100, v10
	ds_bpermute_b32 v95, v100, v11
	ds_bpermute_b32 v96, v100, v16
	ds_bpermute_b32 v97, v100, v17
	ds_bpermute_b32 v98, v100, v18
	ds_bpermute_b32 v99, v100, v19
	s_waitcnt lgkmcnt(7)
; DI float wave_sum(float v) { v += shx(v, 32); v += shx(v, 16); v += shx(v, 8); v += shx(v, 4); v += shx(v, 2); v += shx(v, 1); return v; }
; DI void phase_norm(const float* X, const float* nw, bf16_t* H, const float* Wg, int ldw, int col0, float* GATE, lptr lds) {
;     ...
;             for (int e = 0; e < 8; ++e) g[e] = wave_sum(g[e]);
;             if (lane == 0) { *(f32x4*)(GATE + (size_t)row * 8) = (f32x4){g[0], g[1], g[2], g[3]}; *(f32x4*)(GATE + (size_t)row * 8 + 4) = (f32x4){g[4], g[5], g[6], g[7]}; }
	v_add_f32_e32 v8, v8, v92
	s_waitcnt lgkmcnt(6)
	v_add_f32_e32 v9, v9, v93
	s_waitcnt lgkmcnt(5)
	v_add_f32_e32 v10, v10, v94
	s_waitcnt lgkmcnt(4)
	v_add_f32_e32 v11, v11, v95
	s_waitcnt lgkmcnt(3)
	v_add_f32_e32 v16, v16, v96
	s_waitcnt lgkmcnt(2)
	v_add_f32_e32 v17, v17, v97
	s_waitcnt lgkmcnt(1)
	v_add_f32_e32 v18, v18, v98
	s_waitcnt lgkmcnt(0)
	v_add_f32_e32 v19, v19, v99
	ds_bpermute_b32 v92, v101, v8
	ds_bpermute_b32 v93, v101, v9
	ds_bpermute_b32 v94, v101, v10
	ds_bpermute_b32 v95, v101, v11
	ds_bpermute_b32 v96, v101, v16
	ds_bpermute_b32 v97, v101, v17
	ds_bpermute_b32 v98, v101, v18
	ds_bpermute_b32 v99, v101, v19
	s_waitcnt lgkmcnt(7)
	v_add_f32_e32 v8, v8, v92
	s_waitcnt lgkmcnt(6)
	v_add_f32_e32 v9, v9, v93
	s_waitcnt lgkmcnt(5)
	v_add_f32_e32 v10, v10, v94
	s_waitcnt lgkmcnt(4)
	v_add_f32_e32 v11, v11, v95
	s_waitcnt lgkmcnt(3)
	v_add_f32_e32 v16, v16, v96
	s_waitcnt lgkmcnt(2)
	v_add_f32_e32 v17, v17, v97
	s_waitcnt lgkmcnt(1)
	v_add_f32_e32 v18, v18, v98
	s_waitcnt lgkmcnt(0)
	v_add_f32_e32 v19, v19, v99
	ds_bpermute_b32 v92, v102, v8
	ds_bpermute_b32 v93, v102, v9
	ds_bpermute_b32 v94, v102, v10
	ds_bpermute_b32 v95, v102, v11
	ds_bpermute_b32 v96, v102, v16
	ds_bpermute_b32 v97, v102, v17
	ds_bpermute_b32 v98, v102, v18
	ds_bpermute_b32 v99, v102, v19
	s_waitcnt lgkmcnt(7)
	v_add_f32_e32 v8, v8, v92
	s_waitcnt lgkmcnt(6)
	v_add_f32_e32 v9, v9, v93
	s_waitcnt lgkmcnt(5)
	v_add_f32_e32 v10, v10, v94
	s_waitcnt lgkmcnt(4)
	v_add_f32_e32 v11, v11, v95
	s_waitcnt lgkmcnt(3)
	v_add_f32_e32 v16, v16, v96
	s_waitcnt lgkmcnt(2)
	v_add_f32_e32 v17, v17, v97
	s_waitcnt lgkmcnt(1)
	v_add_f32_e32 v18, v18, v98
	s_waitcnt lgkmcnt(0)
	v_add_f32_e32 v19, v19, v99
	ds_bpermute_b32 v92, v103, v8
	ds_bpermute_b32 v93, v103, v9
	ds_bpermute_b32 v94, v103, v10
	ds_bpermute_b32 v95, v103, v11
	ds_bpermute_b32 v96, v103, v16
	ds_bpermute_b32 v97, v103, v17
	ds_bpermute_b32 v98, v103, v18
	ds_bpermute_b32 v99, v103, v19
	s_waitcnt lgkmcnt(7)
	v_add_f32_e32 v8, v8, v92
	s_waitcnt lgkmcnt(6)
	v_add_f32_e32 v9, v9, v93
	s_waitcnt lgkmcnt(5)
	v_add_f32_e32 v10, v10, v94
	s_waitcnt lgkmcnt(4)
	v_add_f32_e32 v11, v11, v95
	s_waitcnt lgkmcnt(3)
	v_add_f32_e32 v16, v16, v96
	s_waitcnt lgkmcnt(2)
	v_add_f32_e32 v17, v17, v97
	s_waitcnt lgkmcnt(1)
	v_add_f32_e32 v18, v18, v98
	s_waitcnt lgkmcnt(0)
	v_add_f32_e32 v19, v19, v99
	ds_bpermute_b32 v92, v104, v8
	ds_bpermute_b32 v93, v104, v9
	ds_bpermute_b32 v94, v104, v10
	ds_bpermute_b32 v95, v104, v11
	ds_bpermute_b32 v96, v104, v16
	ds_bpermute_b32 v97, v104, v17
	ds_bpermute_b32 v98, v104, v18
	ds_bpermute_b32 v99, v104, v19
	s_waitcnt lgkmcnt(7)
	v_add_f32_e32 v8, v8, v92
	s_waitcnt lgkmcnt(6)
	v_add_f32_e32 v9, v9, v93
	s_waitcnt lgkmcnt(5)
	v_add_f32_e32 v10, v10, v94
	s_waitcnt lgkmcnt(4)
	v_add_f32_e32 v11, v11, v95
	s_waitcnt lgkmcnt(3)
	v_add_f32_e32 v16, v16, v96
	s_waitcnt lgkmcnt(2)
	v_add_f32_e32 v17, v17, v97
	s_waitcnt lgkmcnt(1)
	v_add_f32_e32 v18, v18, v98
	s_waitcnt lgkmcnt(0)
	v_add_f32_e32 v19, v19, v99
	ds_bpermute_b32 v92, v105, v8
	ds_bpermute_b32 v93, v105, v9
	ds_bpermute_b32 v94, v105, v10
	ds_bpermute_b32 v95, v105, v11
	ds_bpermute_b32 v96, v105, v16
	ds_bpermute_b32 v97, v105, v17
	ds_bpermute_b32 v98, v105, v18
	ds_bpermute_b32 v99, v105, v19
	s_waitcnt lgkmcnt(7)
	v_add_f32_e32 v8, v8, v92
	s_waitcnt lgkmcnt(6)
	v_add_f32_e32 v9, v9, v93
	s_waitcnt lgkmcnt(5)
	v_add_f32_e32 v10, v10, v94
	s_waitcnt lgkmcnt(4)
	v_add_f32_e32 v11, v11, v95
	s_waitcnt lgkmcnt(3)
	v_add_f32_e32 v16, v16, v96
	s_waitcnt lgkmcnt(2)
	v_add_f32_e32 v17, v17, v97
	s_waitcnt lgkmcnt(1)
	v_add_f32_e32 v18, v18, v98
	s_waitcnt lgkmcnt(0)
	v_add_f32_e32 v19, v19, v99
	s_and_saveexec_b64 s[0:1], s[38:39]
	s_cbranch_execz .LBB0_92
	v_readlane_b32 s2, v250, 41
	v_lshlrev_b64 v[20:21], 5, v[0:1]
	v_readlane_b32 s3, v250, 42
	s_nop 1
	v_lshl_add_u64 v[20:21], s[2:3], 0, v[20:21]
	global_store_dwordx4 v[20:21], v[8:11], off
	global_store_dwordx4 v[20:21], v[16:19], off offset:16
	s_branch .LBB0_92
